# attention hot loops: dropped redundant m0 save/restore around each LDS-DMA piece (20 SALU per iteration)
# baseline (speedup 1.0000x reference)
.LBB0_523:
	s_add_u32 s50, s46, 0xffffe000
	s_addc_u32 s51, s47, -1
	s_cmp_gt_i32 s14, 2
	s_cselect_b32 s9, -3, 2
	s_add_i32 s9, s9, s14
	s_lshl_b32 s12, s9, 13
	s_add_i32 s12, s12, s77
	s_mov_b32 m0, s12
	s_nop 0
	global_load_lds_dwordx4 v208, s[50:51]
	s_add_u32 s50, s40, 0xffffc000
	s_addc_u32 s51, s41, -1
	s_lshl_b32 s9, s9, 14
	s_add_i32 s9, s9, s61
	s_mov_b32 m0, s9
	s_nop 0
	global_load_lds_dwordx4 v208, s[50:51]
	s_add_u32 s50, s40, 0xffffe000
	s_addc_u32 s51, s41, -1
	s_addk_i32 s9, 0x2000
	s_mov_b32 m0, s9
	s_nop 0
	global_load_lds_dwordx4 v208, s[50:51]
	s_cmp_ge_u32 s67, s55
	s_cselect_b64 s[50:51], -1, 0
	s_and_b64 vcc, exec, s[50:51]
	s_cbranch_vccnz .LBB0_517
.LBB0_524:
	s_cmp_gt_i32 s14, 1
	s_cselect_b32 s9, -2, 3
	s_add_i32 s9, s9, s14
	s_lshl_b32 s12, s9, 13
	s_add_i32 s12, s12, s77
	s_mov_b32 m0, s12
	s_nop 0
	global_load_lds_dwordx4 v208, s[46:47]
	s_lshl_b32 s9, s9, 14
	s_add_i32 s9, s9, s61
	s_mov_b32 m0, s9
	s_nop 0
	global_load_lds_dwordx4 v208, s[40:41]
	s_add_u32 s12, s40, 0x2000
	s_addc_u32 s13, s41, 0
	s_addk_i32 s9, 0x2000
	s_mov_b32 m0, s9
	s_nop 0
	global_load_lds_dwordx4 v208, s[12:13]
	s_sub_i32 s9, s66, 64
	s_cmpk_gt_u32 s9, 0x15c
	s_cbranch_scc0 .LBB0_518
	s_branch .LBB0_519

.LBB0_591:
	v_lshl_add_u32 v136, s8, 13, v135
	ds_read_b128 v[2:5], v136
	ds_read_b128 v[6:9], v136 offset:512
	s_lshl_b32 s12, s54, 14
	v_add_u32_e32 v15, s12, v1
	s_waitcnt lgkmcnt(1)
	v_mfma_f32_32x32x16_bf16 v[96:111], v[2:5], v[124:127], 0
	ds_read_b128 v[10:13], v136 offset:2048
	v_cvt_pk_bf16_f32 v128, v64, v65
	v_cvt_pk_bf16_f32 v129, v66, v67
	s_waitcnt lgkmcnt(1)
	v_mfma_f32_32x32x16_bf16 v[80:95], v[6:9], v[124:127], 0
	ds_read_b128 v[2:5], v136 offset:2560
	v_cvt_pk_bf16_f32 v130, v68, v69
	v_cvt_pk_bf16_f32 v131, v70, v71
	s_waitcnt lgkmcnt(1)
	v_mfma_f32_32x32x16_bf16 v[96:111], v[10:13], v[120:123], v[96:111]
	ds_read_b128 v[6:9], v136 offset:4096
	v_mfma_f32_16x16x32_bf16 v[144:147], v[128:131], v[140:143], v[144:147]
	v_cvt_pk_bf16_f32 v10, v72, v73
	v_cvt_pk_bf16_f32 v11, v74, v75
	s_waitcnt lgkmcnt(1)
	v_mfma_f32_32x32x16_bf16 v[80:95], v[2:5], v[120:123], v[80:95]
	ds_read_b128 v[64:67], v136 offset:4608
	v_cvt_pk_bf16_f32 v12, v76, v77
	v_cvt_pk_bf16_f32 v13, v78, v79
	s_waitcnt lgkmcnt(1)
	v_mfma_f32_32x32x16_bf16 v[96:111], v[6:9], v[116:119], v[96:111]
	ds_read_b128 v[2:5], v136 offset:6144
	v_mfma_f32_16x16x32_bf16 v[144:147], v[10:13], v[140:143], v[144:147]
	v_cvt_pk_bf16_f32 v6, v48, v49
	v_cvt_pk_bf16_f32 v7, v50, v51
	s_waitcnt lgkmcnt(1)
	v_mfma_f32_32x32x16_bf16 v[80:95], v[64:67], v[116:119], v[80:95]
	ds_read_b128 v[68:71], v136 offset:6656
	v_cvt_pk_bf16_f32 v8, v52, v53
	v_cvt_pk_bf16_f32 v9, v54, v55
	s_waitcnt lgkmcnt(1)
	v_mfma_f32_32x32x16_bf16 v[96:111], v[2:5], v[112:115], v[96:111]
	v_cvt_pk_bf16_f32 v2, v56, v57
	v_cvt_pk_bf16_f32 v3, v58, v59
	v_mfma_f32_16x16x32_bf16 v[144:147], v[6:9], v[140:143], v[144:147]
	ds_read_b64_tr_b16 v[48:49], v15
	ds_read_b64_tr_b16 v[50:51], v15 offset:1024
	s_waitcnt lgkmcnt(2)
	v_mfma_f32_32x32x16_bf16 v[80:95], v[68:71], v[112:115], v[80:95]
	v_cvt_pk_bf16_f32 v4, v60, v61
	v_cvt_pk_bf16_f32 v5, v62, v63
	ds_read_b64_tr_b16 v[52:53], v15 offset:512
	ds_read_b64_tr_b16 v[54:55], v15 offset:1536
	s_add_i32 s51, s49, -1
	s_cmp_ge_u32 s51, s48
	s_cbranch_scc1 .LBB0_593
	s_add_u32 s12, s40, 0xffffe000
	s_addc_u32 s13, s41, -1
	s_cmp_gt_i32 s8, 2
	s_cselect_b32 s54, -3, 2
	s_add_i32 s54, s54, s8
	s_lshl_b32 s55, s54, 13
	s_add_i32 s55, s55, s46
	s_mov_b32 m0, s55
	s_nop 0
	global_load_lds_dwordx4 v134, s[12:13]
	s_add_u32 s12, s6, 0xffffe000
	s_addc_u32 s13, s7, -1
	s_lshl_b32 s54, s54, 14
	s_add_i32 s54, s54, s47
	s_mov_b32 m0, s54
	s_nop 0
	global_load_lds_dwordx4 v134, s[12:13]
.LBB0_593:
	s_cmp_ge_u32 s49, s48
	s_cbranch_scc1 .LBB0_590
	s_cmp_gt_i32 s8, 1
	s_cselect_b32 s12, -2, 3
	s_add_i32 s12, s12, s8
	s_lshl_b32 s13, s12, 13
	s_add_i32 s13, s13, s46
	s_mov_b32 m0, s13
	s_nop 0
	global_load_lds_dwordx4 v134, s[40:41]
	s_lshl_b32 s12, s12, 14
	s_add_i32 s12, s12, s47
	s_mov_b32 m0, s12
	s_nop 0
	global_load_lds_dwordx4 v134, s[6:7]
	s_branch .LBB0_590
